# v20 plus P11 epilogue: second batch of row-scale loads issued with the first (spare VGPRs) and SB column-scale prefetch
# baseline (speedup 1.0000x reference)
.LBB0_2162:
	v_lshl_add_u32 v178, s14, 8, v180
	v_or_b32_e32 v174, 16, v178
	v_or_b32_e32 v172, 32, v178
	v_or_b32_e32 v170, 48, v178
	s_mov_b64 s[8:9], -1
	s_cmp_eq_u32 s74, s14
	v_ashrrev_i32_e32 v179, 31, v178
	v_ashrrev_i32_e32 v175, 31, v174
	v_ashrrev_i32_e32 v173, 31, v172
	v_ashrrev_i32_e32 v171, 31, v170
	v_add_u32_e32 v138, 0x80, v178
	v_add_u32_e32 v139, 0x22100, v1
	s_cbranch_scc1 .LBB0_2164
	v_lshlrev_b64 v[2:3], 2, v[178:179]
	v_lshlrev_b64 v[6:7], 2, v[174:175]
	v_lshlrev_b64 v[140:141], 2, v[172:173]
	v_lshl_add_u64 v[4:5], s[28:29], 0, v[2:3]
	v_lshl_add_u64 v[8:9], s[28:29], 0, v[6:7]
	v_lshl_add_u64 v[142:143], s[28:29], 0, v[140:141]
	flat_load_dword v144, v[4:5]
	s_nop 0
	flat_load_dword v245, v[8:9] offset:512
	flat_load_dword v9, v[8:9]
	s_nop 0
	flat_load_dword v246, v[142:143] offset:512
	flat_load_dword v142, v[142:143]
	v_lshl_add_u64 v[2:3], s[20:21], 0, v[2:3]
	flat_load_dword v143, v[2:3]
	v_lshl_add_u64 v[6:7], s[20:21], 0, v[6:7]
	flat_load_dword v145, v[6:7]
	flat_load_dword v247, v[6:7] offset:512
	v_lshl_add_u64 v[6:7], s[20:21], 0, v[140:141]
	flat_load_dword v146, v[6:7]
	flat_load_dword v248, v[6:7] offset:512
	v_lshlrev_b64 v[6:7], 2, v[170:171]
	v_lshl_add_u64 v[140:141], s[20:21], 0, v[6:7]
	v_lshl_add_u64 v[6:7], s[28:29], 0, v[6:7]
	flat_load_dword v147, v[140:141]
	flat_load_dword v249, v[140:141] offset:512
	flat_load_dword v148, v[6:7]
	flat_load_dword v250, v[6:7] offset:512
	flat_load_dword v149, v[4:5] offset:512
	flat_load_dword v150, v[2:3] offset:512
	v_lshl_or_b32 v252, s73, 8, v182
	v_ashrrev_i32_e32 v253, 31, v252
	v_lshl_add_u64 v[252:253], v[252:253], 2, s[30:31]
	flat_load_dword v251, v[252:253]
	flat_load_dword v251, v[252:253] offset:512
	v_add_u32_e32 v8, 0x90, v178
	s_waitcnt vmcnt(0) lgkmcnt(0)
	v_fmamk_f32 v2, v144, 0x39800000, v186
	v_fmamk_f32 v3, v9, 0x39800000, v186
	v_mul_f32_e32 v5, 0x4f800000, v2
	v_cmp_gt_f32_e32 vcc, s71, v2
	v_fmamk_f32 v4, v142, 0x39800000, v186
	v_mul_f32_e32 v6, 0x4f800000, v3
	v_cndmask_b32_e32 v2, v2, v5, vcc
	v_cmp_gt_f32_e64 s[8:9], s71, v3
	v_mul_f32_e32 v7, 0x4f800000, v4
	v_sqrt_f32_e32 v5, v2
	v_cndmask_b32_e64 v3, v3, v6, s[8:9]
	v_cmp_gt_f32_e64 s[10:11], s71, v4
	v_sqrt_f32_e32 v6, v3
	v_add_u32_e32 v9, -1, v5
	v_cndmask_b32_e64 v4, v4, v7, s[10:11]
	v_sqrt_f32_e32 v7, v4
	v_add_u32_e32 v141, -1, v6
	v_fma_f32 v152, -v9, v5, v2
	v_add_u32_e32 v140, 1, v5
	v_add_u32_e32 v144, -1, v7
	v_fma_f32 v168, -v141, v6, v3
	v_cmp_ge_f32_e64 s[12:13], 0, v152
	v_add_u32_e32 v142, 1, v6
	v_fma_f32 v153, -v140, v5, v2
	v_fma_f32 v176, -v144, v7, v4
	v_cndmask_b32_e64 v5, v5, v9, s[12:13]
	v_cmp_ge_f32_e64 s[12:13], 0, v168
	v_add_u32_e32 v151, 1, v7
	v_fma_f32 v169, -v142, v6, v3
	v_cndmask_b32_e64 v6, v6, v141, s[12:13]
	v_cmp_ge_f32_e64 s[12:13], 0, v176
	v_fma_f32 v177, -v151, v7, v4
	s_nop 0
	v_cndmask_b32_e64 v7, v7, v144, s[12:13]
	v_cmp_lt_f32_e64 s[12:13], 0, v153
	s_nop 1
	v_cndmask_b32_e64 v5, v5, v140, s[12:13]
	v_cmp_lt_f32_e64 s[12:13], 0, v169
	v_mul_f32_e32 v9, 0x37800000, v5
	v_cndmask_b32_e32 v5, v5, v9, vcc
	v_cndmask_b32_e64 v6, v6, v142, s[12:13]
	v_cmp_lt_f32_e64 s[12:13], 0, v177
	v_mul_f32_e32 v140, 0x37800000, v6
	v_cmp_class_f32_e32 vcc, v2, v187
	v_cndmask_b32_e64 v7, v7, v151, s[12:13]
	v_mul_f32_e32 v141, 0x37800000, v7
	v_cndmask_b32_e64 v6, v6, v140, s[8:9]
	v_cndmask_b32_e32 v2, v5, v2, vcc
	v_cmp_class_f32_e32 vcc, v3, v187
	v_cndmask_b32_e64 v7, v7, v141, s[10:11]
	s_nop 0
	v_cndmask_b32_e32 v3, v6, v3, vcc
	v_cmp_class_f32_e32 vcc, v4, v187
	v_div_scale_f32 v6, s[8:9], v3, v3, v145
	s_nop 0
	v_cndmask_b32_e32 v144, v7, v4, vcc
	v_div_scale_f32 v4, s[8:9], v2, v2, v143
	v_rcp_f32_e32 v9, v4
	v_rcp_f32_e32 v140, v6
	v_div_scale_f32 v5, vcc, v143, v2, v143
	v_fma_f32 v141, -v4, v9, 1.0
	v_fma_f32 v142, -v6, v140, 1.0
	v_fmac_f32_e32 v9, v141, v9
	v_div_scale_f32 v7, s[10:11], v145, v3, v145
	v_fmac_f32_e32 v140, v142, v140
	v_mul_f32_e32 v141, v5, v9
	v_mul_f32_e32 v142, v7, v140
	v_fma_f32 v169, -v4, v141, v5
	v_fma_f32 v176, -v6, v142, v7
	v_fmac_f32_e32 v141, v169, v9
	v_fmac_f32_e32 v142, v176, v140
	v_fma_f32 v4, -v4, v141, v5
	v_fma_f32 v5, -v6, v142, v7
	v_div_fmas_f32 v4, v4, v9, v141
	s_mov_b64 vcc, s[10:11]
	v_div_fixup_f32 v2, v4, v2, v143
	v_div_fmas_f32 v4, v5, v140, v142
	v_ashrrev_i32_e32 v9, 31, v8
	v_div_fixup_f32 v3, v4, v3, v145
	v_lshlrev_b64 v[4:5], 2, v[8:9]
	v_lshl_add_u64 v[6:7], s[20:21], 0, v[4:5]
	v_lshl_add_u64 v[4:5], s[28:29], 0, v[4:5]
	v_mov_b32_e32 v145, v245
	v_add_u32_e32 v4, 0xa0, v178
	v_add_u32_e32 v140, 0xb0, v178
	v_ashrrev_i32_e32 v5, 31, v4
	v_ashrrev_i32_e32 v141, 31, v140
	v_lshlrev_b64 v[4:5], 2, v[4:5]
	v_lshlrev_b64 v[140:141], 2, v[140:141]
	v_lshl_add_u64 v[8:9], s[20:21], 0, v[4:5]
	v_lshl_add_u64 v[142:143], s[20:21], 0, v[140:141]
	v_lshl_add_u64 v[140:141], s[28:29], 0, v[140:141]
	v_lshl_add_u64 v[4:5], s[28:29], 0, v[4:5]
	v_mov_b32_e32 v7, v247
	s_nop 0
	v_mov_b32_e32 v8, v248
	s_nop 0
	v_mov_b32_e32 v9, v246
	s_nop 0
	v_mov_b32_e32 v142, v249
	s_nop 0
	v_mov_b32_e32 v140, v250
	v_fmamk_f32 v4, v148, 0x39800000, v186
	v_mul_f32_e32 v5, 0x4f800000, v4
	v_cmp_gt_f32_e32 vcc, s71, v4
	v_div_scale_f32 v151, s[8:9], v144, v144, v146
	s_nop 0
	v_cndmask_b32_e32 v4, v4, v5, vcc
	v_sqrt_f32_e32 v5, v4
	v_rcp_f32_e32 v152, v151
	v_div_scale_f32 v153, s[8:9], v146, v144, v146
	v_add_u32_e32 v141, -1, v5
	v_fma_f32 v143, -v141, v5, v4
	v_cmp_ge_f32_e64 s[10:11], 0, v143
	v_add_u32_e32 v143, 1, v5
	v_fma_f32 v168, -v151, v152, 1.0
	v_cndmask_b32_e64 v141, v5, v141, s[10:11]
	v_fma_f32 v5, -v143, v5, v4
	v_cmp_lt_f32_e64 s[10:11], 0, v5
	v_fmac_f32_e32 v152, v168, v152
	v_mul_f32_e32 v168, v153, v152
	v_cndmask_b32_e64 v5, v141, v143, s[10:11]
	v_mul_f32_e32 v141, 0x37800000, v5
	v_cndmask_b32_e32 v5, v5, v141, vcc
	v_cmp_class_f32_e32 vcc, v4, v187
	v_fma_f32 v6, -v151, v168, v153
	v_fmac_f32_e32 v168, v6, v152
	v_cndmask_b32_e32 v5, v5, v4, vcc
	v_div_scale_f32 v141, s[10:11], v5, v5, v147
	v_rcp_f32_e32 v143, v141
	v_fma_f32 v6, -v151, v168, v153
	s_mov_b64 vcc, s[8:9]
	v_div_fmas_f32 v4, v6, v152, v168
	v_fma_f32 v6, -v141, v143, 1.0
	v_fmac_f32_e32 v143, v6, v143
	v_div_scale_f32 v6, vcc, v147, v5, v147
	v_div_fixup_f32 v4, v4, v144, v146
	v_mul_f32_e32 v144, v6, v143
	v_fma_f32 v146, -v141, v144, v6
	v_fmac_f32_e32 v144, v146, v143
	v_fmamk_f32 v146, v149, 0x39800000, v186
	v_mul_f32_e32 v148, 0x4f800000, v146
	v_cmp_gt_f32_e64 s[8:9], s71, v146
	v_fma_f32 v6, -v141, v144, v6
	v_div_fmas_f32 v6, v6, v143, v144
	v_cndmask_b32_e64 v146, v146, v148, s[8:9]
	v_sqrt_f32_e32 v148, v146
	v_div_fixup_f32 v5, v6, v5, v147
	v_add_u32_e32 v168, 0x80, v178
	v_ashrrev_i32_e32 v169, 31, v168
	v_add_u32_e32 v141, -1, v148
	v_fma_f32 v143, -v141, v148, v146
	v_cmp_ge_f32_e32 vcc, 0, v143
	v_add_u32_e32 v143, 1, v148
	v_fma_f32 v144, -v143, v148, v146
	v_cndmask_b32_e32 v141, v148, v141, vcc
	v_cmp_lt_f32_e32 vcc, 0, v144
	v_mov_b64_e32 v[176:177], v[168:169]
	s_waitcnt vmcnt(0) lgkmcnt(0)
	v_fmamk_f32 v145, v145, 0x39800000, v186
	v_cndmask_b32_e32 v141, v141, v143, vcc
	v_mul_f32_e32 v143, 0x37800000, v141
	v_cndmask_b32_e64 v141, v141, v143, s[8:9]
	v_cmp_class_f32_e32 vcc, v146, v187
	v_mul_f32_e32 v147, 0x4f800000, v145
	v_fmamk_f32 v9, v9, 0x39800000, v186
	v_cndmask_b32_e32 v141, v141, v146, vcc
	v_div_scale_f32 v143, s[8:9], v141, v141, v150
	v_rcp_f32_e32 v144, v143
	v_cmp_gt_f32_e64 s[8:9], s71, v145
	v_fmamk_f32 v140, v140, 0x39800000, v186
	v_fma_f32 v6, -v143, v144, 1.0
	v_cndmask_b32_e64 v145, v145, v147, s[8:9]
	v_fmac_f32_e32 v144, v6, v144
	v_div_scale_f32 v6, vcc, v150, v141, v150
	v_sqrt_f32_e32 v147, v145
	v_mul_f32_e32 v146, v6, v144
	v_fma_f32 v148, -v143, v146, v6
	v_fmac_f32_e32 v146, v148, v144
	v_fma_f32 v6, -v143, v146, v6
	v_add_u32_e32 v143, -1, v147
	v_fma_f32 v148, -v143, v147, v145
	v_cmp_ge_f32_e64 s[10:11], 0, v148
	v_add_u32_e32 v148, 1, v147
	v_div_fmas_f32 v6, v6, v144, v146
	v_cndmask_b32_e64 v143, v147, v143, s[10:11]
	v_fma_f32 v147, -v148, v147, v145
	v_cmp_lt_f32_e64 s[10:11], 0, v147
	v_mul_f32_e32 v146, 0x4f800000, v9
	v_div_fixup_f32 v6, v6, v141, v150
	v_cndmask_b32_e64 v143, v143, v148, s[10:11]
	v_mul_f32_e32 v147, 0x37800000, v143
	v_cndmask_b32_e64 v143, v143, v147, s[8:9]
	v_cmp_class_f32_e64 s[8:9], v145, v187
	s_nop 1
	v_cndmask_b32_e64 v143, v143, v145, s[8:9]
	v_div_scale_f32 v145, s[8:9], v143, v143, v7
	v_rcp_f32_e32 v147, v145
	v_cmp_gt_f32_e64 s[8:9], s71, v9
	v_fma_f32 v141, -v145, v147, 1.0
	s_nop 0
	v_cndmask_b32_e64 v9, v9, v146, s[8:9]
	v_fmac_f32_e32 v147, v141, v147
	v_div_scale_f32 v141, vcc, v7, v143, v7
	v_sqrt_f32_e32 v146, v9
	v_mul_f32_e32 v144, v141, v147
	v_fma_f32 v148, -v145, v144, v141
	v_fmac_f32_e32 v144, v148, v147
	v_fma_f32 v141, -v145, v144, v141
	v_add_u32_e32 v145, -1, v146
	v_fma_f32 v148, -v145, v146, v9
	v_cmp_ge_f32_e64 s[10:11], 0, v148
	v_add_u32_e32 v148, 1, v146
	v_div_fmas_f32 v141, v141, v147, v144
	v_cndmask_b32_e64 v145, v146, v145, s[10:11]
	v_fma_f32 v146, -v148, v146, v9
	v_cmp_lt_f32_e64 s[10:11], 0, v146
	v_mul_f32_e32 v144, 0x4f800000, v140
	v_div_fixup_f32 v7, v141, v143, v7
	v_cndmask_b32_e64 v145, v145, v148, s[10:11]
	v_mul_f32_e32 v146, 0x37800000, v145
	v_cndmask_b32_e64 v145, v145, v146, s[8:9]
	v_cmp_class_f32_e64 s[8:9], v9, v187
	s_nop 1
	v_cndmask_b32_e64 v9, v145, v9, s[8:9]
	v_div_scale_f32 v145, s[8:9], v9, v9, v8
	v_rcp_f32_e32 v146, v145
	v_cmp_gt_f32_e64 s[8:9], s71, v140
	v_fma_f32 v141, -v145, v146, 1.0
	s_nop 0
	v_cndmask_b32_e64 v140, v140, v144, s[8:9]
	v_fmac_f32_e32 v146, v141, v146
	v_div_scale_f32 v141, vcc, v8, v9, v8
	v_sqrt_f32_e32 v144, v140
	v_mul_f32_e32 v143, v141, v146
	v_fma_f32 v147, -v145, v143, v141
	v_fmac_f32_e32 v143, v147, v146
	v_fma_f32 v141, -v145, v143, v141
	v_add_u32_e32 v145, -1, v144
	v_fma_f32 v147, -v145, v144, v140
	v_cmp_ge_f32_e64 s[10:11], 0, v147
	v_add_u32_e32 v147, 1, v144
	v_div_fmas_f32 v141, v141, v146, v143
	v_cndmask_b32_e64 v145, v144, v145, s[10:11]
	v_fma_f32 v144, -v147, v144, v140
	v_cmp_lt_f32_e64 s[10:11], 0, v144
	v_div_fixup_f32 v8, v141, v9, v8
	s_nop 0
	v_cndmask_b32_e64 v144, v145, v147, s[10:11]
	v_mul_f32_e32 v145, 0x37800000, v144
	v_cndmask_b32_e64 v144, v144, v145, s[8:9]
	v_cmp_class_f32_e64 s[8:9], v140, v187
	s_nop 1
	v_cndmask_b32_e64 v140, v144, v140, s[8:9]
	v_div_scale_f32 v144, s[8:9], v140, v140, v142
	v_rcp_f32_e32 v145, v144
	s_mov_b64 s[8:9], 0
	v_fma_f32 v9, -v144, v145, 1.0
	v_fmac_f32_e32 v145, v9, v145
	v_div_scale_f32 v9, vcc, v142, v140, v142
	v_mul_f32_e32 v141, v9, v145
	v_fma_f32 v143, -v144, v141, v9
	v_fmac_f32_e32 v141, v143, v145
	v_fma_f32 v9, -v144, v141, v9
	v_div_fmas_f32 v9, v9, v145, v141
	v_div_fixup_f32 v9, v9, v140, v142
	ds_write_b128 v139, v[2:5]
	ds_write_b128 v139, v[6:9] offset:16

	.amdhsa_kernel _Z6mk_fwd4Args
		.amdhsa_group_segment_fixed_size 0
		.amdhsa_private_segment_fixed_size 0
		.amdhsa_kernarg_size 488
		.amdhsa_user_sgpr_count 2
		.amdhsa_user_sgpr_dispatch_ptr 0
		.amdhsa_user_sgpr_queue_ptr 0
		.amdhsa_user_sgpr_kernarg_segment_ptr 1
		.amdhsa_user_sgpr_dispatch_id 0
		.amdhsa_user_sgpr_kernarg_preload_length 0
		.amdhsa_user_sgpr_kernarg_preload_offset 0
		.amdhsa_user_sgpr_private_segment_size 0
		.amdhsa_uses_dynamic_stack 0
		.amdhsa_enable_private_segment 0
		.amdhsa_system_sgpr_workgroup_id_x 1
		.amdhsa_system_sgpr_workgroup_id_y 0
		.amdhsa_system_sgpr_workgroup_id_z 0
		.amdhsa_system_sgpr_workgroup_info 0
		.amdhsa_system_vgpr_workitem_id 0
		.amdhsa_next_free_vgpr 256
		.amdhsa_next_free_sgpr 98
		.amdhsa_accum_offset 256
		.amdhsa_reserve_vcc 1
		.amdhsa_float_round_mode_32 0
		.amdhsa_float_round_mode_16_64 0
		.amdhsa_float_denorm_mode_32 3
		.amdhsa_float_denorm_mode_16_64 3
		.amdhsa_dx10_clamp 1
		.amdhsa_ieee_mode 1
		.amdhsa_fp16_overflow 0
		.amdhsa_tg_split 0
		.amdhsa_exception_fp_ieee_invalid_op 0
		.amdhsa_exception_fp_denorm_src 0
		.amdhsa_exception_fp_ieee_div_zero 0
		.amdhsa_exception_fp_ieee_overflow 0
		.amdhsa_exception_fp_ieee_underflow 0
		.amdhsa_exception_fp_ieee_inexact 0
		.amdhsa_exception_int_div_zero 0
	.end_amdhsa_kernel

amdhsa.kernels:
  - .agpr_count:     0
    .args:
      - .offset:         0
        .size:           232
        .value_kind:     by_value
      - .offset:         232
        .size:           4
        .value_kind:     hidden_block_count_x
      - .offset:         236
        .size:           4
        .value_kind:     hidden_block_count_y
      - .offset:         240
        .size:           4
        .value_kind:     hidden_block_count_z
      - .offset:         244
        .size:           2
        .value_kind:     hidden_group_size_x
      - .offset:         246
        .size:           2
        .value_kind:     hidden_group_size_y
      - .offset:         248
        .size:           2
        .value_kind:     hidden_group_size_z
      - .offset:         250
        .size:           2
        .value_kind:     hidden_remainder_x
      - .offset:         252
        .size:           2
        .value_kind:     hidden_remainder_y
      - .offset:         254
        .size:           2
        .value_kind:     hidden_remainder_z
      - .offset:         272
        .size:           8
        .value_kind:     hidden_global_offset_x
      - .offset:         280
        .size:           8
        .value_kind:     hidden_global_offset_y
      - .offset:         288
        .size:           8
        .value_kind:     hidden_global_offset_z
      - .offset:         296
        .size:           2
        .value_kind:     hidden_grid_dims
      - .offset:         352
        .size:           4
        .value_kind:     hidden_dynamic_lds_size
    .group_segment_fixed_size: 0
    .kernarg_segment_align: 8
    .kernarg_segment_size: 488
    .language:       OpenCL C
    .language_version:
      - 2
      - 0
    .max_flat_workgroup_size: 512
    .name:           _Z6mk_fwd4Args
    .private_segment_fixed_size: 0
    .sgpr_count:     104
    .sgpr_spill_count: 21
    .symbol:         _Z6mk_fwd4Args.kd
    .uniform_work_group_size: 1
    .uses_dynamic_stack: false
    .vgpr_count:     256
    .vgpr_spill_count: 0
    .wavefront_size: 64
